# same stack, w2 split moved to item 0x3c80 (11 transposer items per wave stay in the in-proj tail)
# speedup vs baseline: 1.0043x; 1.0031x over previous
; __device__ __forceinline__ int lane_id() { int l; asm volatile("v_mbcnt_lo_u32_b32 %0, -1, 0\n\tv_mbcnt_hi_u32_b32 %0, -1, %0" : "=v"(l)); return l; }
; #define LAS __attribute__((address_space(3)))
; __device__ __forceinline__ void phase_wconv_rest(const Params& p, LAS unsigned char* lds, int gw, int NGW) {
;     const int lane = lane_id(), wave = p.wave_id;
;     LAS float* scr = (LAS float*)(lds + 16384 + wave * 16384);
;     constexpr int I_A = (WA / 64) * (D_MODEL / 32), I_O = (D_MODEL / 64) * (D_MODEL / 32), I_1 = (D_MODEL / 64) * (FFN / 32), I_2 = (FFN / 64) * (D_MODEL / 32);
;     constexpr int NITEMS = 2 * I_A + I_O + 2 * I_1 + I_2;
;     unsigned char* ws = p.ws;
;     const float* sh2 = (const float*)(ws + WS_MOD) + 3 * D_MODEL; float* b2 = (float*)(ws + WS_BIAS2);
;     for (int it = gw; it < NITEMS; it += NGW) {
;         int r = it;
;         if (r < I_A) { transpose_item<false, false>(p.w_a, WA, D_MODEL, (bf16*)(ws + WS_WAT), 0, scr, r, lane); continue; } r -= I_A;
;         if (r < I_A) { transpose_item<false, false>(p.w_b, WA, D_MODEL, (bf16*)(ws + WS_WBT), 0, scr, r, lane); continue; } r -= I_A;
;         if (r < I_O) { transpose_item<false, false>(p.w_o, D_MODEL, D_MODEL, (bf16*)(ws + WS_WOT), 0, scr, r, lane); continue; } r -= I_O;
;         if (r < I_1) { transpose_item<false, true>(p.w1, D_MODEL, FFN, (bf16*)(ws + WS_W13T), 0, scr, r, lane, sh2, b2); continue; } r -= I_1;
;         if (r < I_1) { transpose_item<false, true>(p.w3, D_MODEL, FFN, (bf16*)(ws + WS_W13T), 128, scr, r, lane, sh2, b2); continue; } r -= I_1;
;         transpose_item<false, false>(p.w2, FFN, D_MODEL, (bf16*)(ws + WS_W2T), 0, scr, r, lane);
;     }
; __global__ void __launch_bounds__(NTHREADS, 2) mega_fwd(Params p_in) {
;     ...
;       const int nfree = nb - CTX_UNITS;
;       if (nfree >= 64) { if (bx >= CTX_UNITS) phase_wconv_rest(p, lds, (bx - CTX_UNITS) * 8 + wave_id, nfree * 8); }
.LBB0_240:
	s_cmpk_lt_i32 s2, 0x50
	s_cbranch_scc1 .LBB0_268
	s_lshl_b32 s4, s2, 3
	s_add_i32 s4, s4, s3
	s_add_i32 s20, s4, 0xfffffd80
	s_movk_i32 s98, 0x51ff
	s_cmpk_lg_i32 s33, 0x100
	s_cselect_b32 s98, s98, 0x3c7f
	s_cmp_gt_i32 s20, s98
	v_mbcnt_lo_u32_b32 v0, -1, 0
	v_mbcnt_hi_u32_b32 v0, -1, v0
	s_cbranch_scc1 .LBB0_268
	s_add_i32 s21, s46, 0xfffffd80
	s_waitcnt lgkmcnt(0)
	s_add_u32 s6, s22, 0x106000
	s_addc_u32 s7, s23, 0
	s_add_u32 s16, s22, 0x18000
	s_addc_u32 s17, s23, 0
	s_lshl_b32 s3, s3, 14
	v_ashrrev_i32_e32 v34, 5, v0
	v_lshlrev_b32_e32 v1, 2, v0
	s_movk_i32 s4, 0x84
	s_add_i32 s3, s3, 0
	v_and_b32_e32 v22, 0x7c, v1
	v_mul_lo_u32 v1, v34, s4
	v_add3_u32 v26, s3, v22, v1
	v_lshlrev_b32_e32 v1, 3, v0
	v_and_b32_e32 v1, 56, v1
	v_ashrrev_i32_e32 v35, 3, v0
	v_lshlrev_b32_e32 v12, 1, v1
	v_mov_b32_e32 v13, 0
	v_mul_u32_u24_e32 v4, 0x84, v1
	v_lshl_add_u64 v[10:11], s[22:23], 0, v[12:13]
	v_lshlrev_b32_e32 v1, 2, v35
	s_mov_b64 s[22:23], 0x142000
	v_add3_u32 v27, s3, v4, v1
	v_lshl_add_u64 v[4:5], v[10:11], 0, s[22:23]
	s_mov_b64 s[22:23], 0x4b42000
	v_lshl_add_u64 v[6:7], v[10:11], 0, s[22:23]
	s_mov_b64 s[22:23], 0x4742000
	s_mov_b64 s[4:5], 0x2d42000
	v_ashrrev_i32_e32 v1, 31, v0
	v_lshl_add_u64 v[8:9], v[10:11], 0, s[22:23]
	s_mov_b64 s[22:23], 0x4342000
	v_mov_b32_e32 v23, v13
	s_mov_b32 s19, 0
	v_lshl_add_u64 v[2:3], v[10:11], 0, s[4:5]
	v_add_u32_e32 v36, 8, v35
	v_add_u32_e32 v37, 16, v35
	v_add_u32_e32 v38, 24, v35
	v_cmp_gt_i32_e64 s[4:5], 32, v0
	v_lshl_add_u64 v[10:11], v[10:11], 0, s[22:23]
	v_lshl_add_u64 v[12:13], s[42:43], 0, v[22:23]
	v_lshl_add_u64 v[14:15], s[40:41], 0, v[22:23]
	v_lshl_add_u64 v[16:17], s[14:15], 0, v[22:23]
	v_lshl_add_u64 v[18:19], s[12:13], 0, v[22:23]
	v_lshl_add_u64 v[20:21], s[10:11], 0, v[22:23]
	v_lshl_add_u64 v[22:23], s[8:9], 0, v[22:23]
	v_lshl_add_u64 v[24:25], v[0:1], 2, s[16:17]
	s_lshl_b32 s3, s20, 5
	s_lshl_b32 s12, s21, 5
	s_mov_b32 s13, 0xc000
	s_mov_b32 s14, 0x18000
	s_mov_b32 s15, 0x24000
	s_movk_i32 s22, 0x2c00
	s_movk_i32 s23, 0x5800
	v_add_u32_e32 v39, 0x4000, v26
	v_add_u32_e32 v40, 0x4400, v26
	v_add_u32_e32 v41, 0x4800, v26
	v_add_u32_e32 v42, 0x4c00, v26
	v_add_u32_e32 v43, 0x5000, v26
	v_add_u32_e32 v44, 0x5400, v26
	v_add_u32_e32 v45, 0x5800, v26
	v_add_u32_e32 v46, 0x5c00, v26
	v_add_u32_e32 v47, 0x4000, v27
	s_branch .LBB0_244

; __device__ __forceinline__ int lane_id() { int l; asm volatile("v_mbcnt_lo_u32_b32 %0, -1, 0\n\tv_mbcnt_hi_u32_b32 %0, -1, %0" : "=v"(l)); return l; }
; #define LAS __attribute__((address_space(3)))
; __device__ __forceinline__ void phase_wconv_rest(const Params& p, LAS unsigned char* lds, int gw, int NGW) {
;     const int lane = lane_id(), wave = p.wave_id;
;     LAS float* scr = (LAS float*)(lds + 16384 + wave * 16384);
;     constexpr int I_A = (WA / 64) * (D_MODEL / 32), I_O = (D_MODEL / 64) * (D_MODEL / 32), I_1 = (D_MODEL / 64) * (FFN / 32), I_2 = (FFN / 64) * (D_MODEL / 32);
;     constexpr int NITEMS = 2 * I_A + I_O + 2 * I_1 + I_2;
;     unsigned char* ws = p.ws;
;     const float* sh2 = (const float*)(ws + WS_MOD) + 3 * D_MODEL; float* b2 = (float*)(ws + WS_BIAS2);
;     for (int it = gw; it < NITEMS; it += NGW) {
;         int r = it;
;         if (r < I_A) { transpose_item<false, false>(p.w_a, WA, D_MODEL, (bf16*)(ws + WS_WAT), 0, scr, r, lane); continue; } r -= I_A;
;         if (r < I_A) { transpose_item<false, false>(p.w_b, WA, D_MODEL, (bf16*)(ws + WS_WBT), 0, scr, r, lane); continue; } r -= I_A;
;         if (r < I_O) { transpose_item<false, false>(p.w_o, D_MODEL, D_MODEL, (bf16*)(ws + WS_WOT), 0, scr, r, lane); continue; } r -= I_O;
;         if (r < I_1) { transpose_item<false, true>(p.w1, D_MODEL, FFN, (bf16*)(ws + WS_W13T), 0, scr, r, lane, sh2, b2); continue; } r -= I_1;
;         if (r < I_1) { transpose_item<false, true>(p.w3, D_MODEL, FFN, (bf16*)(ws + WS_W13T), 128, scr, r, lane, sh2, b2); continue; } r -= I_1;
;         transpose_item<false, false>(p.w2, FFN, D_MODEL, (bf16*)(ws + WS_W2T), 0, scr, r, lane);
;     }
; __global__ void __launch_bounds__(NTHREADS, 2) mega_fwd(Params p_in) {
;     ...
;       const int nfree = nb - CTX_UNITS;
;       if (nfree >= 64) { if (bx >= CTX_UNITS) phase_wconv_rest(p, lds, (bx - CTX_UNITS) * 8 + wave_id, nfree * 8); }
;       else phase_wconv_rest(p, lds, bx * 8 + wave_id, nb * 8); }
.LBB0_505:
	s_cmpk_lg_i32 s33, 0x100
	s_cbranch_scc1 .Lw2_skip
	s_cmpk_lt_i32 s2, 0x40
	s_cbranch_scc1 .Lw2_skip
	v_writelane_b32 v250, s3, 40
	v_writelane_b32 v250, s12, 41
	v_writelane_b32 v250, s18, 42
	v_writelane_b32 v250, s19, 43
	v_writelane_b32 v250, s20, 44
	v_writelane_b32 v250, s21, 45
	v_writelane_b32 v250, s22, 46
	v_writelane_b32 v250, s23, 47
	v_writelane_b32 v250, s24, 48
	v_writelane_b32 v250, s25, 49
	v_writelane_b32 v250, s26, 50
	v_writelane_b32 v250, s27, 51
	s_lshr_b32 s3, s76, 6
	s_load_dwordx8 s[8:15], s[0:1], 0x70
	s_load_dwordx2 s[40:41], s[0:1], 0x90
	s_load_dwordx2 s[42:43], s[0:1], 0xa8
	s_load_dwordx2 s[22:23], s[0:1], 0xb8
	s_waitcnt vmcnt(0) lgkmcnt(0)
	s_barrier
	s_lshl_b32 s4, s2, 3
	s_add_i32 s4, s4, s3
	s_add_i32 s20, s4, 0x3a80
	s_cmpk_gt_i32 s20, 0x51ff
	v_mbcnt_lo_u32_b32 v0, -1, 0
	v_mbcnt_hi_u32_b32 v0, -1, v0
	s_cbranch_scc1 .Lw2_done
	s_movk_i32 s21, 0x600
	s_waitcnt lgkmcnt(0)
	s_add_u32 s6, s22, 0x106000
	s_addc_u32 s7, s23, 0
	s_add_u32 s16, s22, 0x18000
	s_addc_u32 s17, s23, 0
	s_lshl_b32 s3, s3, 14
	v_ashrrev_i32_e32 v34, 5, v0
	v_lshlrev_b32_e32 v1, 2, v0
	s_movk_i32 s4, 0x84
	s_add_i32 s3, s3, 0
	v_and_b32_e32 v22, 0x7c, v1
	v_mul_lo_u32 v1, v34, s4
	v_add3_u32 v26, s3, v22, v1
	v_lshlrev_b32_e32 v1, 3, v0
	v_and_b32_e32 v1, 56, v1
	v_ashrrev_i32_e32 v35, 3, v0
	v_lshlrev_b32_e32 v12, 1, v1
	v_mov_b32_e32 v13, 0
	v_mul_u32_u24_e32 v4, 0x84, v1
	v_lshl_add_u64 v[10:11], s[22:23], 0, v[12:13]
	v_lshlrev_b32_e32 v1, 2, v35
	s_mov_b64 s[22:23], 0x142000
	v_add3_u32 v27, s3, v4, v1
	v_lshl_add_u64 v[4:5], v[10:11], 0, s[22:23]
	s_mov_b64 s[22:23], 0x4b42000
	v_lshl_add_u64 v[6:7], v[10:11], 0, s[22:23]
	s_mov_b64 s[22:23], 0x4742000
	s_mov_b64 s[4:5], 0x2d42000
	v_ashrrev_i32_e32 v1, 31, v0
	v_lshl_add_u64 v[8:9], v[10:11], 0, s[22:23]
	s_mov_b64 s[22:23], 0x4342000
	v_mov_b32_e32 v23, v13
	s_mov_b32 s19, 0
	v_lshl_add_u64 v[2:3], v[10:11], 0, s[4:5]
	v_add_u32_e32 v36, 8, v35
	v_add_u32_e32 v37, 16, v35
	v_add_u32_e32 v38, 24, v35
	v_cmp_gt_i32_e64 s[4:5], 32, v0
	v_lshl_add_u64 v[10:11], v[10:11], 0, s[22:23]
	v_lshl_add_u64 v[12:13], s[42:43], 0, v[22:23]
	v_lshl_add_u64 v[14:15], s[40:41], 0, v[22:23]
	v_lshl_add_u64 v[16:17], s[14:15], 0, v[22:23]
	v_lshl_add_u64 v[18:19], s[12:13], 0, v[22:23]
	v_lshl_add_u64 v[20:21], s[10:11], 0, v[22:23]
	v_lshl_add_u64 v[22:23], s[8:9], 0, v[22:23]
	v_lshl_add_u64 v[24:25], v[0:1], 2, s[16:17]
	s_lshl_b32 s3, s20, 5
	s_lshl_b32 s12, s21, 5
	s_mov_b32 s13, 0xc000
	s_mov_b32 s14, 0x18000
	s_mov_b32 s15, 0x24000
	s_movk_i32 s22, 0x2c00
	s_movk_i32 s23, 0x5800
	v_add_u32_e32 v39, 0x4000, v26
	v_add_u32_e32 v40, 0x4400, v26
	v_add_u32_e32 v41, 0x4800, v26
	v_add_u32_e32 v42, 0x4c00, v26
	v_add_u32_e32 v43, 0x5000, v26
	v_add_u32_e32 v44, 0x5400, v26
	v_add_u32_e32 v45, 0x5800, v26
	v_add_u32_e32 v46, 0x5c00, v26
	v_add_u32_e32 v47, 0x4000, v27
	s_branch .Lw2c_244
